# MLA attention loop: 16 per-tile packed-P hand-off v_mov removed (packs write the consumer registers; copies paid once on loop exit)
# speedup vs baseline: 1.0131x; 1.0131x over previous
.LBB0_635:
	s_or_b64 exec, exec, s[8:9]
	global_load_dwordx4 v[162:165], v[184:185], off
	s_add_i32 s8, s10, -1
	s_and_b32 s11, s8, 1
	s_mul_i32 s8, s11, 0x3400
	v_add_u32_e32 v174, s8, v196
	ds_read_b128 v[80:83], v174
	ds_read_b128 v[204:207], v174 offset:32
	ds_read_b128 v[208:211], v174 offset:6656
	ds_read_b128 v[214:217], v174 offset:6688
	s_xor_b32 s8, s11, 1
	s_mulk_i32 s8, 0x3000
	v_add_u32_e32 v176, s8, v198
	s_waitcnt lgkmcnt(3)
	v_mfma_f32_32x32x16_bf16 v[96:111], v[80:83], v[142:145], v[48:63]
	ds_read_b128 v[222:225], v174 offset:64
	ds_read_b64_tr_b16 v[226:227], v176 offset:26624
	ds_read_b64_tr_b16 v[228:229], v176 offset:28160
	s_waitcnt lgkmcnt(4)
	v_mfma_f32_32x32x16_bf16 v[80:95], v[208:211], v[142:145], v[48:63]
	ds_read_b128 v[208:211], v174 offset:6720
	ds_read_b64_tr_b16 v[230:231], v176 offset:26688
	ds_read_b64_tr_b16 v[232:233], v176 offset:28224
	v_mfma_f32_32x32x16_bf16 v[96:111], v[204:207], v[138:141], v[96:111]
	ds_read_b128 v[204:207], v174 offset:96
	ds_read_b64_tr_b16 v[234:235], v176 offset:29696
	ds_read_b64_tr_b16 v[236:237], v176 offset:31232
	s_waitcnt lgkmcnt(9)
	v_mfma_f32_32x32x16_bf16 v[80:95], v[214:217], v[138:141], v[80:95]
	ds_read_b128 v[214:217], v174 offset:6752
	ds_read_b64_tr_b16 v[238:239], v176 offset:29760
	ds_read_b64_tr_b16 v[240:241], v176 offset:31296
	s_waitcnt lgkmcnt(11)
	v_mfma_f32_32x32x16_bf16 v[96:111], v[222:225], v[134:137], v[96:111]
	ds_read_b128 v[222:225], v174 offset:128
	ds_read_b64_tr_b16 v[242:243], v176 offset:32768
	ds_read_b64_tr_b16 v[244:245], v176 offset:34304
	s_waitcnt lgkmcnt(11)
	v_mfma_f32_32x32x16_bf16 v[80:95], v[208:211], v[134:137], v[80:95]
	ds_read_b128 v[208:211], v174 offset:6784
	ds_read_b64_tr_b16 v[246:247], v176 offset:32832
	ds_read_b64_tr_b16 v[248:249], v176 offset:34368
	s_waitcnt lgkmcnt(11)
	v_mfma_f32_32x32x16_bf16 v[96:111], v[204:207], v[130:133], v[96:111]
	ds_read_b128 v[204:207], v174 offset:160
	ds_read_b64_tr_b16 v[186:187], v176 offset:35840
	ds_read_b64_tr_b16 v[188:189], v176 offset:37376
	s_waitcnt lgkmcnt(11)
	v_mfma_f32_32x32x16_bf16 v[80:95], v[214:217], v[130:133], v[80:95]
	ds_read_b128 v[214:217], v174 offset:6816
	ds_read_b64_tr_b16 v[174:175], v176 offset:35904
	ds_read_b64_tr_b16 v[176:177], v176 offset:37440
	s_waitcnt lgkmcnt(11)
	v_mfma_f32_32x32x16_bf16 v[96:111], v[222:225], v[120:123], v[96:111]
	s_waitcnt lgkmcnt(8)
	v_mfma_f32_32x32x16_bf16 v[80:95], v[208:211], v[120:123], v[80:95]
	s_waitcnt lgkmcnt(5)
	v_mfma_f32_32x32x16_bf16 v[96:111], v[204:207], v[116:119], v[96:111]
	s_waitcnt lgkmcnt(2)
	v_mfma_f32_32x32x16_bf16 v[80:95], v[214:217], v[116:119], v[80:95]
	v_mfma_f32_32x32x16_bf16 v[32:47], v[226:229], v[158:161], v[32:47]
	v_mfma_f32_32x32x16_bf16 v[16:31], v[230:233], v[158:161], v[16:31]
	v_mfma_f32_32x32x16_bf16 v[32:47], v[234:237], v[154:157], v[32:47]
	v_mfma_f32_32x32x16_bf16 v[16:31], v[238:241], v[154:157], v[16:31]
	v_mfma_f32_32x32x16_bf16 v[32:47], v[242:245], v[150:153], v[32:47]
	v_mfma_f32_32x32x16_bf16 v[16:31], v[246:249], v[150:153], v[16:31]
	v_mfma_f32_32x32x16_bf16 v[32:47], v[186:189], v[146:149], v[32:47]
	s_waitcnt lgkmcnt(0)
	v_mfma_f32_32x32x16_bf16 v[16:31], v[174:177], v[146:149], v[16:31]
	s_bitcmp1_b32 s10, 0
	s_cselect_b32 s8, 0x3400, 0
	s_add_i32 s16, s8, 0
	v_add_u32_e32 v174, s16, v194
	s_waitcnt vmcnt(1)
	ds_write_b128 v174, v[166:169]
	s_and_saveexec_b64 s[8:9], s[0:1]
	v_add_u32_e32 v166, s16, v195
	ds_write_b128 v166, v[124:127]
	s_or_b64 exec, exec, s[8:9]
	v_mfma_f32_32x32x16_bf16 v[64:79], v[112:115], v[158:161], v[64:79]
	v_exp_f32_e32 v166, v96
	v_exp_f32_e32 v167, v97
	v_exp_f32_e32 v98, v98
	v_exp_f32_e32 v99, v99
	v_exp_f32_e32 v168, v100
	v_exp_f32_e32 v169, v101
	v_exp_f32_e32 v174, v102
	v_mfma_f32_32x32x16_bf16 v[64:79], v[112:115], v[154:157], v[64:79]
	v_exp_f32_e32 v175, v103
	v_exp_f32_e32 v104, v104
	v_exp_f32_e32 v176, v105
	v_exp_f32_e32 v105, v106
	v_exp_f32_e32 v177, v107
	v_exp_f32_e32 v106, v108
	v_exp_f32_e32 v108, v109
	v_mfma_f32_32x32x16_bf16 v[64:79], v[112:115], v[150:153], v[64:79]
	v_exp_f32_e32 v107, v110
	v_exp_f32_e32 v109, v111
	v_exp_f32_e32 v80, v80
	v_exp_f32_e32 v81, v81
	v_exp_f32_e32 v82, v82
	v_exp_f32_e32 v83, v83
	v_exp_f32_e32 v84, v84
	v_mfma_f32_32x32x16_bf16 v[64:79], v[112:115], v[146:149], v[64:79]
	v_exp_f32_e32 v85, v85
	v_exp_f32_e32 v86, v86
	v_exp_f32_e32 v87, v87
	v_exp_f32_e32 v88, v88
	v_exp_f32_e32 v89, v89
	v_exp_f32_e32 v90, v90
	v_exp_f32_e32 v91, v91
	v_exp_f32_e32 v92, v92
	v_exp_f32_e32 v93, v93
	v_exp_f32_e32 v94, v94
	v_exp_f32_e32 v95, v95
	s_mulk_i32 s11, 0x3000
	s_add_i32 s10, s10, 1
	s_mov_b64 s[8:9], 0x2000
	v_cvt_pk_bf16_f32 v147, v90, v91
	v_cvt_pk_bf16_f32 v146, v88, v89
	v_cvt_pk_bf16_f32 v153, v86, v87
	v_cvt_pk_bf16_f32 v152, v84, v85
	v_cvt_pk_bf16_f32 v151, v82, v83
	v_cvt_pk_bf16_f32 v150, v80, v81
	v_cvt_pk_bf16_f32 v157, v107, v109
	v_cvt_pk_bf16_f32 v156, v106, v108
	v_cvt_pk_bf16_f32 v155, v105, v177
	v_cvt_pk_bf16_f32 v154, v104, v176
	v_cvt_pk_bf16_f32 v161, v174, v175
	v_cvt_pk_bf16_f32 v160, v168, v169
	v_cvt_pk_bf16_f32 v159, v98, v99
	v_cvt_pk_bf16_f32 v158, v166, v167
	v_cvt_pk_bf16_f32 v148, v92, v93
	v_cvt_pk_bf16_f32 v149, v94, v95
	v_add_u32_e32 v80, s11, v197
	v_lshl_add_u64 v[184:185], v[184:185], 0, s[8:9]
	v_lshl_add_u64 v[190:191], v[190:191], 0, s[92:93]
	s_cmpk_eq_i32 s10, 0x80
	v_lshl_add_u64 v[192:193], v[192:193], 0, s[92:93]
	s_waitcnt vmcnt(0)
	ds_write_b128 v80, v[162:165] offset:26624
	s_waitcnt lgkmcnt(0)
	s_barrier
	s_cbranch_scc1 .LBB0_639
	global_load_dwordx4 v[166:169], v[190:191], off
	s_and_saveexec_b64 s[8:9], s[0:1]
	s_cbranch_execnz .LBB0_634
	s_branch .LBB0_635
.LBB0_639:
	v_mov_b32_e32 v108, v158
	v_mov_b32_e32 v109, v159
	v_mov_b32_e32 v110, v160
	v_mov_b32_e32 v111, v161
	v_mov_b32_e32 v104, v154
	v_mov_b32_e32 v105, v155
	v_mov_b32_e32 v106, v156
	v_mov_b32_e32 v107, v157
	v_mov_b32_e32 v100, v150
	v_mov_b32_e32 v101, v151
	v_mov_b32_e32 v102, v152
	v_mov_b32_e32 v103, v153
	v_mov_b32_e32 v96, v146
	v_mov_b32_e32 v97, v147
	v_mov_b32_e32 v98, v148
	v_mov_b32_e32 v99, v149
	s_add_u32 s6, s6, 0x17d000
	s_addc_u32 s7, s7, 0
	v_lshl_add_u64 v[80:81], s[6:7], 0, v[128:129]
	global_load_dwordx4 v[150:153], v[80:81], off
	s_and_saveexec_b64 s[8:9], s[0:1]
	s_cbranch_execz .LBB0_641
	v_lshl_add_u64 v[80:81], s[6:7], 0, v[172:173]
	global_load_dwordx4 v[124:127], v[80:81], off
